# attn loop staging: 64-bit global-load addresses formed with v_lshl_add_u64 and an SGPR pair instead of v_add_co/v_addc + nops (-6 instructions per 2 tiles, no vcc use)
# speedup vs baseline: 1.0133x; 1.0050x over previous
; __device__ __forceinline__ void finishSM(f32x16& p0, f32x16& p1, float alpha, float& l_reg, bf16x8& pa0, bf16x8& pa1, bf16x8& pa2, bf16x8& pa3) {
; #pragma unroll
;   for (int r = 0; r < 16; ++r) p1[r] = __builtin_amdgcn_exp2f(p1[r]);
;   float ps = 0;
; #pragma unroll
;   for (int r = 0; r < 16; ++r) ps += p0[r];
; #pragma unroll
;   for (int r = 0; r < 16; ++r) ps += p1[r];
;   { auto rr = __builtin_amdgcn_permlane32_swap(__float_as_uint(ps), __float_as_uint(ps), false, false);
;     ps = __uint_as_float(rr[0]) + __uint_as_float(rr[1]); }
;   l_reg = l_reg * alpha + ps;
;     ...
;   PK4(p0, 0, pa0); PK4(p0, 8, pa1); PK4(p1, 0, pa2); PK4(p1, 8, pa3);
;     ...
; }
; __device__ __forceinline__ void qkt(f32x16& p0, f32x16& p1, const char* Ks, const bf16x8* qr, const char* qrl, int r32, int hi) {
;   p0 = f32x16{}; p1 = f32x16{};
; #pragma unroll
;   for (int d0 = 0; d0 < 8; ++d0) { int cb = (d0 * 16 + hi * 8) * 2;
;     bf16x8 b0 = *reinterpret_cast<const bf16x8*>(Ks + KSWZ(r32, cb));
;     bf16x8 b1 = *reinterpret_cast<const bf16x8*>(Ks + KSWZ(32 + r32, cb));
;     p0 = __builtin_amdgcn_mfma_f32_32x32x16_bf16(b0, qr[d0], p0, 0, 0, 0);
;     p1 = __builtin_amdgcn_mfma_f32_32x32x16_bf16(b1, qr[d0], p1, 0, 0, 0); }
; #pragma unroll
;   for (int d0 = 8; d0 < 12; ++d0) { int cb = (d0 * 16 + hi * 8) * 2;
;     bf16x8 b0 = *reinterpret_cast<const bf16x8*>(Ks + KSWZ(r32, cb));
;     bf16x8 b1 = *reinterpret_cast<const bf16x8*>(Ks + KSWZ(32 + r32, cb));
;     bf16x8 qf = *reinterpret_cast<const bf16x8*>(qrl + (((2 * (d0 - 8) + hi) ^ ((r32 >> 1) & 7)) << 4));
;     p0 = __builtin_amdgcn_mfma_f32_32x32x16_bf16(b0, qf, p0, 0, 0, 0);
;     p1 = __builtin_amdgcn_mfma_f32_32x32x16_bf16(b1, qf, p1, 0, 0, 0); }
; }
.LBB0_1151:
	s_sub_i32 s30, s76, 1
	s_cmp_eq_u32 s76, 0
	s_cselect_b32 s30, 2, s30
	s_add_i32 s18, s76, 1
	s_cmp_lg_u32 s76, 2
	s_cselect_b32 s18, s18, 0
	ds_read_b128 v[232:235], v199 offset:36864
	ds_read_b128 v[236:239], v199 offset:49152
	ds_read_b128 v[240:243], v205 offset:36864
	ds_read_b128 v[248:251], v205 offset:49152
	ds_read_b128 v[244:247], v206 offset:36864
	v_exp_f32_e32 v162, v162
	v_add_f32_e32 v211, v225, v228
	v_exp_f32_e32 v163, v163
	v_add_f32_e32 v211, v226, v211
	v_exp_f32_e32 v160, v160
	s_waitcnt lgkmcnt(3)
	v_mfma_f32_32x32x16_bf16 v[80:95], v[232:235], v[124:127], 0
	ds_read_b128 v[232:235], v206 offset:49152
	v_add_f32_e32 v211, v229, v211
	v_exp_f32_e32 v161, v161
	v_add_f32_e32 v211, v227, v211
	v_exp_f32_e32 v158, v158
	v_mfma_f32_32x32x16_bf16 v[64:79], v[236:239], v[124:127], 0
	ds_read_b128 v[236:239], v208 offset:36864
	v_add_f32_e32 v211, v230, v211
	v_exp_f32_e32 v159, v159
	v_add_f32_e32 v211, v223, v211
	v_exp_f32_e32 v156, v156
	s_waitcnt lgkmcnt(3)
	v_mfma_f32_32x32x16_bf16 v[80:95], v[240:243], v[120:123], v[80:95]
	ds_read_b128 v[240:243], v208 offset:49152
	v_add_f32_e32 v211, v224, v211
	v_exp_f32_e32 v157, v157
	v_add_f32_e32 v211, v219, v211
	v_exp_f32_e32 v154, v154
	v_mfma_f32_32x32x16_bf16 v[64:79], v[248:251], v[120:123], v[64:79]
	ds_read_b128 v[248:251], v207 offset:36864
	v_add_f32_e32 v211, v221, v211
	v_exp_f32_e32 v155, v155
	v_add_f32_e32 v211, v220, v211
	v_exp_f32_e32 v152, v152
	s_waitcnt lgkmcnt(3)
	v_mfma_f32_32x32x16_bf16 v[80:95], v[244:247], v[116:119], v[80:95]
	ds_read_b128 v[244:247], v207 offset:49152
	v_add_f32_e32 v211, v222, v211
	v_exp_f32_e32 v153, v153
	v_add_f32_e32 v211, v215, v211
	v_exp_f32_e32 v150, v150
	v_mfma_f32_32x32x16_bf16 v[64:79], v[232:235], v[116:119], v[64:79]
	ds_read_b128 v[232:235], v204 offset:36864
	v_add_f32_e32 v211, v217, v211
	v_exp_f32_e32 v151, v151
	v_add_f32_e32 v211, v216, v211
	v_exp_f32_e32 v148, v148
	s_waitcnt lgkmcnt(3)
	v_mfma_f32_32x32x16_bf16 v[80:95], v[236:239], v[112:115], v[80:95]
	ds_read_b128 v[236:239], v204 offset:49152
	v_add_f32_e32 v211, v218, v211
	v_exp_f32_e32 v149, v149
	v_add_f32_e32 v212, v162, v163
	v_add_f32_e32 v212, v160, v212
	v_add_f32_e32 v212, v161, v212
	v_mfma_f32_32x32x16_bf16 v[64:79], v[240:243], v[112:115], v[64:79]
	ds_read_b128 v[240:243], v203 offset:36864
	v_add_f32_e32 v212, v158, v212
	v_add_f32_e32 v212, v159, v212
	v_add_f32_e32 v212, v156, v212
	v_add_f32_e32 v212, v157, v212
	v_add_f32_e32 v212, v154, v212
	v_add_f32_e32 v212, v155, v212
	s_waitcnt lgkmcnt(3)
	v_mfma_f32_32x32x16_bf16 v[80:95], v[248:251], v[108:111], v[80:95]
	ds_read_b128 v[248:251], v203 offset:49152
	v_add_f32_e32 v212, v152, v212
	v_add_f32_e32 v212, v153, v212
	v_add_f32_e32 v212, v150, v212
	v_add_f32_e32 v212, v151, v212
	v_add_f32_e32 v212, v148, v212
	v_add_f32_e32 v212, v149, v212
	v_mfma_f32_32x32x16_bf16 v[64:79], v[244:247], v[108:111], v[64:79]
	ds_read_b128 v[244:247], v200 offset:36864
	v_add_f32_e32 v211, v211, v212
	v_mov_b32_e32 v212, v211
	s_lshl_b32 s19, s18, 14
	v_add_u32_e32 v231, s19, v183
	s_waitcnt vmcnt(0)
	ds_write_b128 v231, v[140:143]
	v_add_u32_e32 v140, s19, v184
	ds_write_b128 v140, v[144:147]
	ds_write_b128 v185, v[136:139] offset:12288
	s_waitcnt lgkmcnt(6)
	v_mfma_f32_32x32x16_bf16 v[80:95], v[232:235], v[104:107], v[80:95]
	ds_read_b128 v[232:235], v200 offset:49152
	ds_write_b128 v185, v[132:135] offset:24576
	s_mov_b32 s18, 0xfffa0000
	ds_write_b128 v186, v[128:131] offset:12288
	s_mov_b32 s19, -1
	v_lshl_add_u64 v[128:129], v[168:169], 0, s[18:19]
	s_mov_b32 s18, 0xfffc0000
	v_lshl_add_u64 v[130:131], v[168:169], 0, s[18:19]
	global_load_dwordx4 v[140:143], v[128:129], off
	global_load_dwordx4 v[136:139], v[128:129], off offset:-256
	v_mfma_f32_32x32x16_bf16 v[64:79], v[236:239], v[104:107], v[64:79]
	ds_read_b128 v[236:239], v191 offset:36864
	global_load_dwordx4 v[144:147], v[130:131], off
	global_load_dwordx4 v[132:135], v[130:131], off offset:-256
	s_movk_i32 s18, 0xe000
	v_lshl_add_u64 v[128:129], v[166:167], 0, s[18:19]
	global_load_dwordx4 v[128:131], v[128:129], off
	v_cvt_pk_bf16_f32 v158, v158, v159
	v_cvt_pk_bf16_f32 v159, v156, v157
	s_waitcnt lgkmcnt(8)
; __device__ __forceinline__ void partialSM(f32x16& p0, f32x16& p1, float& m_reg, float& mn, float& alpha) {
;     ...
;   for (int r = 1; r < 16; ++r) pmax = fmaxf(pmax, p0[r]);
; #pragma unroll
;   for (int r = 0; r < 16; ++r) pmax = fmaxf(pmax, p1[r]);
;   { auto rr = __builtin_amdgcn_permlane32_swap(__float_as_uint(pmax), __float_as_uint(pmax), false, false);
;     pmax = fmaxf(__uint_as_float(rr[0]), __uint_as_float(rr[1])); }
;   if (__builtin_expect(__all(pmax - m_reg <= THR / SCALE), 1)) { mn = m_reg; alpha = 1.f; }
;   else { mn = fmaxf(m_reg, pmax); alpha = __builtin_amdgcn_exp2f((m_reg - mn) * C); m_reg = mn; }
;   float mnC = -mn * C;
; #pragma unroll
;   for (int r = 0; r < 16; ++r) p0[r] = fmaf(p0[r], C, mnC);
; #pragma unroll
;   for (int r = 0; r < 16; ++r) p1[r] = fmaf(p1[r], C, mnC);
; #pragma unroll
;   for (int r = 0; r < 16; ++r) p0[r] = __builtin_amdgcn_exp2f(p0[r]);
; }
; __device__ __forceinline__ void finishSM(f32x16& p0, f32x16& p1, float alpha, float& l_reg, bf16x8& pa0, bf16x8& pa1, bf16x8& pa2, bf16x8& pa3) {
; #pragma unroll
;   for (int r = 0; r < 16; ++r) p1[r] = __builtin_amdgcn_exp2f(p1[r]);
;   float ps = 0;
; #pragma unroll
;   for (int r = 0; r < 16; ++r) ps += p0[r];
; #pragma unroll
;   for (int r = 0; r < 16; ++r) ps += p1[r];
;   { auto rr = __builtin_amdgcn_permlane32_swap(__float_as_uint(ps), __float_as_uint(ps), false, false);
;     ps = __uint_as_float(rr[0]) + __uint_as_float(rr[1]); }
;   l_reg = l_reg * alpha + ps;
;     ...
;   PK4(p0, 0, pa0); PK4(p0, 8, pa1); PK4(p1, 0, pa2); PK4(p1, 8, pa3);
;     ...
; }
; __device__ __forceinline__ void qkt(f32x16& p0, f32x16& p1, const char* Ks, const bf16x8* qr, const char* qrl, int r32, int hi) {
;   p0 = f32x16{}; p1 = f32x16{};
; #pragma unroll
;   for (int d0 = 0; d0 < 8; ++d0) { int cb = (d0 * 16 + hi * 8) * 2;
;     bf16x8 b0 = *reinterpret_cast<const bf16x8*>(Ks + KSWZ(r32, cb));
;     bf16x8 b1 = *reinterpret_cast<const bf16x8*>(Ks + KSWZ(32 + r32, cb));
;     p0 = __builtin_amdgcn_mfma_f32_32x32x16_bf16(b0, qr[d0], p0, 0, 0, 0);
;     p1 = __builtin_amdgcn_mfma_f32_32x32x16_bf16(b1, qr[d0], p1, 0, 0, 0); }
; #pragma unroll
;   for (int d0 = 8; d0 < 12; ++d0) { int cb = (d0 * 16 + hi * 8) * 2;
;     bf16x8 b0 = *reinterpret_cast<const bf16x8*>(Ks + KSWZ(r32, cb));
;     bf16x8 b1 = *reinterpret_cast<const bf16x8*>(Ks + KSWZ(32 + r32, cb));
	v_mfma_f32_32x32x16_bf16 v[80:95], v[240:243], v[100:103], v[80:95]
	ds_read_b128 v[240:243], v202 offset:49152
	v_permlane32_swap_b32_e32 v211, v212
	v_cvt_pk_bf16_f32 v156, v162, v163
	v_cvt_pk_bf16_f32 v157, v160, v161
	v_cvt_pk_bf16_f32 v160, v154, v155
	v_cvt_pk_bf16_f32 v161, v152, v153
	v_cvt_pk_bf16_f32 v162, v150, v151
	v_mfma_f32_32x32x16_bf16 v[64:79], v[248:251], v[100:103], v[64:79]
	ds_read_b128 v[248:251], v182
	v_cvt_pk_bf16_f32 v163, v148, v149
	v_add_f32_e32 v211, v211, v212
	v_cvt_pk_bf16_f32 v148, v225, v228
	v_cvt_pk_bf16_f32 v149, v226, v229
	v_cvt_pk_bf16_f32 v150, v227, v230
	v_cvt_pk_bf16_f32 v151, v223, v224
	s_waitcnt lgkmcnt(5)
	v_mfma_f32_32x32x16_bf16 v[80:95], v[244:247], v[96:99], v[80:95]
	ds_read_b128 v[244:247], v198 offset:36864
	v_cvt_pk_bf16_f32 v152, v219, v221
	v_cvt_pk_bf16_f32 v153, v220, v222
	v_cvt_pk_bf16_f32 v154, v215, v217
	v_cvt_pk_bf16_f32 v155, v216, v218
	v_fma_f32 v176, v209, v176, v211
	v_mfma_f32_32x32x16_bf16 v[64:79], v[232:235], v[96:99], v[64:79]
	ds_read_b128 v[232:235], v201 offset:49152
	s_waitcnt lgkmcnt(2)
	v_mfma_f32_32x32x16_bf16 v[80:95], v[236:239], v[248:251], v[80:95]
	ds_read_b128 v[236:239], v181
	v_mfma_f32_32x32x16_bf16 v[64:79], v[240:243], v[248:251], v[64:79]
	ds_read_b128 v[240:243], v187 offset:36864
	ds_read_b128 v[248:251], v189 offset:49152
	s_waitcnt lgkmcnt(2)
	v_mfma_f32_32x32x16_bf16 v[80:95], v[244:247], v[236:239], v[80:95]
	ds_read_b128 v[244:247], v179
	v_mfma_f32_32x32x16_bf16 v[64:79], v[232:235], v[236:239], v[64:79]
	ds_read_b128 v[232:235], v188 offset:36864
	ds_read_b128 v[236:239], v190 offset:49152
	s_waitcnt lgkmcnt(2)
	v_mfma_f32_32x32x16_bf16 v[80:95], v[240:243], v[244:247], v[80:95]
	ds_read_b128 v[240:243], v177
	v_mfma_f32_32x32x16_bf16 v[64:79], v[248:251], v[244:247], v[64:79]
	s_waitcnt lgkmcnt(0)
	v_mfma_f32_32x32x16_bf16 v[80:95], v[232:235], v[240:243], v[80:95]
	v_mfma_f32_32x32x16_bf16 v[64:79], v[236:239], v[240:243], v[64:79]
	s_lshl_b32 s31, s30, 14
	v_add_u32_e32 v180, s31, v178
	ds_read_b64_tr_b16 v[232:233], v180 offset:0
	ds_read_b64_tr_b16 v[234:235], v180 offset:2048
	ds_read_b64_tr_b16 v[236:237], v180 offset:512
	ds_read_b64_tr_b16 v[238:239], v180 offset:2560
	ds_read_b64_tr_b16 v[240:241], v180 offset:1024
	ds_read_b64_tr_b16 v[242:243], v180 offset:3072
	ds_read_b64_tr_b16 v[248:249], v180 offset:1536
	ds_read_b64_tr_b16 v[250:251], v180 offset:3584
	ds_read_b64_tr_b16 v[244:245], v180 offset:4096
	ds_read_b64_tr_b16 v[246:247], v180 offset:6144
	s_nop 3
	v_max3_f32 v194, v80, v81, v82
	v_max3_f32 v195, v64, v65, v66
	v_max3_f32 v194, v194, v83, v84
	v_max3_f32 v195, v195, v67, v68
	s_waitcnt lgkmcnt(6)
	v_mfma_f32_32x32x16_bf16 v[32:47], v[148:151], v[232:235], v[32:47]
	ds_read_b64_tr_b16 v[232:233], v180 offset:4608
	ds_read_b64_tr_b16 v[234:235], v180 offset:6656
	v_max3_f32 v194, v194, v85, v86
	v_max3_f32 v195, v195, v69, v70
	v_max3_f32 v194, v194, v87, v88
	v_max3_f32 v195, v195, v71, v72
	v_mfma_f32_32x32x16_bf16 v[48:63], v[148:151], v[236:239], v[48:63]
	ds_read_b64_tr_b16 v[236:237], v180 offset:5120
	ds_read_b64_tr_b16 v[238:239], v180 offset:7168
	v_max3_f32 v194, v194, v89, v90
	v_max3_f32 v195, v195, v73, v74
	v_max3_f32 v194, v194, v91, v92
	v_max3_f32 v195, v195, v75, v76
	s_waitcnt lgkmcnt(6)
	v_mfma_f32_32x32x16_bf16 v[16:31], v[148:151], v[240:243], v[16:31]
	ds_read_b64_tr_b16 v[240:241], v180 offset:5632
	ds_read_b64_tr_b16 v[242:243], v180 offset:7680
	v_max3_f32 v194, v194, v93, v94
	v_max3_f32 v195, v195, v77, v78
	v_max3_f32 v194, v194, v95, v195
	v_max_f32_e32 v194, v194, v79
	v_mfma_f32_32x32x16_bf16 v[0:15], v[148:151], v[248:251], v[0:15]
	ds_read_b64_tr_b16 v[248:249], v180 offset:8192
	ds_read_b64_tr_b16 v[250:251], v180 offset:10240
	v_mov_b32_e32 v195, v194
	s_nop 1
	v_permlane32_swap_b32_e32 v194, v195
	v_max_f32_e32 v194, v194, v195
	s_waitcnt lgkmcnt(6)
	v_mfma_f32_32x32x16_bf16 v[32:47], v[152:155], v[244:247], v[32:47]
	ds_read_b64_tr_b16 v[244:245], v180 offset:8704
	ds_read_b64_tr_b16 v[246:247], v180 offset:10752
	v_sub_f32_e32 v195, v194, v210
	v_cmp_ge_f32_e32 vcc, s15, v195
	v_mfma_f32_32x32x16_bf16 v[48:63], v[152:155], v[232:235], v[48:63]
	ds_read_b64_tr_b16 v[232:233], v180 offset:9216
	ds_read_b64_tr_b16 v[234:235], v180 offset:11264
	s_cmp_eq_u64 vcc, exec
	s_cselect_b64 s[40:41], -1, 0
	s_cbranch_scc1 .Lattn_fast1p
	v_max_f32_e32 v194, v210, v194
	v_sub_f32_e32 v195, v210, v194
	v_mul_f32_e32 v195, 0x3dd53b94, v195
	v_exp_f32_e32 v214, v195
	v_mov_b32_e32 v210, v194
	s_branch .Lattn_join1p

; __device__ __forceinline__ void finishSM(f32x16& p0, f32x16& p1, float alpha, float& l_reg, bf16x8& pa0, bf16x8& pa1, bf16x8& pa2, bf16x8& pa3) {
; #pragma unroll
;   for (int r = 0; r < 16; ++r) p1[r] = __builtin_amdgcn_exp2f(p1[r]);
;   float ps = 0;
; #pragma unroll
;   for (int r = 0; r < 16; ++r) ps += p0[r];
; #pragma unroll
;   for (int r = 0; r < 16; ++r) ps += p1[r];
;   { auto rr = __builtin_amdgcn_permlane32_swap(__float_as_uint(ps), __float_as_uint(ps), false, false);
;     ps = __uint_as_float(rr[0]) + __uint_as_float(rr[1]); }
;   l_reg = l_reg * alpha + ps;
;     ...
;   PK4(p0, 0, pa0); PK4(p0, 8, pa1); PK4(p1, 0, pa2); PK4(p1, 8, pa3);
;     ...
; }
; __device__ __forceinline__ void qkt(f32x16& p0, f32x16& p1, const char* Ks, const bf16x8* qr, const char* qrl, int r32, int hi) {
;   p0 = f32x16{}; p1 = f32x16{};
; #pragma unroll
;   for (int d0 = 0; d0 < 8; ++d0) { int cb = (d0 * 16 + hi * 8) * 2;
;     bf16x8 b0 = *reinterpret_cast<const bf16x8*>(Ks + KSWZ(r32, cb));
;     bf16x8 b1 = *reinterpret_cast<const bf16x8*>(Ks + KSWZ(32 + r32, cb));
;     p0 = __builtin_amdgcn_mfma_f32_32x32x16_bf16(b0, qr[d0], p0, 0, 0, 0);
;     p1 = __builtin_amdgcn_mfma_f32_32x32x16_bf16(b1, qr[d0], p1, 0, 0, 0); }
; #pragma unroll
;   for (int d0 = 8; d0 < 12; ++d0) { int cb = (d0 * 16 + hi * 8) * 2;
;     bf16x8 b0 = *reinterpret_cast<const bf16x8*>(Ks + KSWZ(r32, cb));
;     bf16x8 b1 = *reinterpret_cast<const bf16x8*>(Ks + KSWZ(32 + r32, cb));
;     bf16x8 qf = *reinterpret_cast<const bf16x8*>(qrl + (((2 * (d0 - 8) + hi) ^ ((r32 >> 1) & 7)) << 4));
;     p0 = __builtin_amdgcn_mfma_f32_32x32x16_bf16(b0, qf, p0, 0, 0, 0);
;     p1 = __builtin_amdgcn_mfma_f32_32x32x16_bf16(b1, qf, p1, 0, 0, 0); }
; }
.Lattn_skip_rs1p:
	v_exp_f32_e32 v225, v225
	v_exp_f32_e32 v228, v228
	v_exp_f32_e32 v226, v226
	v_add_f32_e32 v211, v225, v228
	s_waitcnt lgkmcnt(3)
	v_mfma_f32_32x32x16_bf16 v[80:95], v[236:239], v[124:127], 0
	ds_read_b128 v[236:239], v206 offset:24576
	v_exp_f32_e32 v229, v229
	v_add_f32_e32 v211, v226, v211
	v_exp_f32_e32 v227, v227
	v_add_f32_e32 v211, v229, v211
	v_mfma_f32_32x32x16_bf16 v[64:79], v[240:243], v[124:127], 0
	ds_read_b128 v[240:243], v208 offset:12288
	v_exp_f32_e32 v230, v230
	v_add_f32_e32 v211, v227, v211
	v_exp_f32_e32 v223, v223
	v_add_f32_e32 v211, v230, v211
	s_waitcnt lgkmcnt(3)
	v_mfma_f32_32x32x16_bf16 v[80:95], v[248:251], v[120:123], v[80:95]
	ds_read_b128 v[248:251], v208 offset:24576
	v_exp_f32_e32 v224, v224
	v_add_f32_e32 v211, v223, v211
	v_exp_f32_e32 v219, v219
	v_add_f32_e32 v211, v224, v211
	v_mfma_f32_32x32x16_bf16 v[64:79], v[244:247], v[120:123], v[64:79]
	ds_read_b128 v[244:247], v207 offset:12288
	v_exp_f32_e32 v221, v221
	v_add_f32_e32 v211, v219, v211
	v_exp_f32_e32 v220, v220
	v_add_f32_e32 v211, v221, v211
	s_waitcnt lgkmcnt(3)
	v_mfma_f32_32x32x16_bf16 v[80:95], v[232:235], v[116:119], v[80:95]
	ds_read_b128 v[232:235], v207 offset:24576
	v_exp_f32_e32 v222, v222
	v_add_f32_e32 v211, v220, v211
	v_exp_f32_e32 v215, v215
	v_add_f32_e32 v211, v222, v211
	v_mfma_f32_32x32x16_bf16 v[64:79], v[236:239], v[116:119], v[64:79]
	ds_read_b128 v[236:239], v204 offset:12288
	v_exp_f32_e32 v217, v217
	v_add_f32_e32 v211, v215, v211
	v_exp_f32_e32 v216, v216
	v_add_f32_e32 v211, v217, v211
	s_waitcnt lgkmcnt(3)
	v_mfma_f32_32x32x16_bf16 v[80:95], v[240:243], v[112:115], v[80:95]
	ds_read_b128 v[240:243], v204 offset:24576
	v_exp_f32_e32 v218, v218
	v_add_f32_e32 v211, v216, v211
	v_exp_f32_e32 v162, v162
	v_add_f32_e32 v211, v218, v211
	v_mfma_f32_32x32x16_bf16 v[64:79], v[248:251], v[112:115], v[64:79]
	ds_read_b128 v[248:251], v203 offset:12288
	v_exp_f32_e32 v163, v163
	v_exp_f32_e32 v160, v160
	v_exp_f32_e32 v161, v161
	s_waitcnt lgkmcnt(3)
	v_mfma_f32_32x32x16_bf16 v[80:95], v[244:247], v[108:111], v[80:95]
	ds_read_b128 v[244:247], v203 offset:24576
	v_exp_f32_e32 v158, v158
	v_exp_f32_e32 v159, v159
	v_exp_f32_e32 v156, v156
	v_mfma_f32_32x32x16_bf16 v[64:79], v[232:235], v[108:111], v[64:79]
	ds_read_b128 v[232:235], v200 offset:12288
	v_exp_f32_e32 v157, v157
	v_exp_f32_e32 v154, v154
	v_exp_f32_e32 v155, v155
	s_waitcnt lgkmcnt(3)
	v_mfma_f32_32x32x16_bf16 v[80:95], v[236:239], v[104:107], v[80:95]
	ds_read_b128 v[236:239], v200 offset:24576
	v_exp_f32_e32 v152, v152
	v_exp_f32_e32 v153, v153
	v_exp_f32_e32 v150, v150
	v_mfma_f32_32x32x16_bf16 v[64:79], v[240:243], v[104:107], v[64:79]
	ds_read_b128 v[240:243], v191 offset:12288
	v_exp_f32_e32 v151, v151
	v_exp_f32_e32 v148, v148
	v_exp_f32_e32 v149, v149
	s_waitcnt lgkmcnt(3)
	v_mfma_f32_32x32x16_bf16 v[80:95], v[248:251], v[100:103], v[80:95]
	ds_read_b128 v[248:251], v202 offset:24576
	v_add_f32_e32 v212, v162, v163
	v_add_f32_e32 v212, v160, v212
	v_add_f32_e32 v212, v161, v212
	v_add_f32_e32 v212, v158, v212
	v_add_f32_e32 v212, v159, v212
	v_add_f32_e32 v212, v156, v212
	v_mfma_f32_32x32x16_bf16 v[64:79], v[244:247], v[100:103], v[64:79]
	ds_read_b128 v[244:247], v182
	v_add_f32_e32 v212, v157, v212
	v_add_f32_e32 v212, v154, v212
	v_add_f32_e32 v212, v155, v212
	v_add_f32_e32 v212, v152, v212
	v_add_f32_e32 v212, v153, v212
	v_add_f32_e32 v212, v150, v212
	s_waitcnt lgkmcnt(3)
	v_mfma_f32_32x32x16_bf16 v[80:95], v[232:235], v[96:99], v[80:95]
	ds_read_b128 v[232:235], v198 offset:12288
	v_add_f32_e32 v212, v151, v212
	v_add_f32_e32 v212, v148, v212
	v_add_f32_e32 v212, v149, v212
	v_add_f32_e32 v211, v211, v212
	v_mov_b32_e32 v212, v211
	v_add_u32_e32 v194, s31, v183
	s_waitcnt vmcnt(4)
	v_mfma_f32_32x32x16_bf16 v[64:79], v[236:239], v[96:99], v[64:79]
	ds_read_b128 v[236:239], v201 offset:24576
	ds_write_b128 v194, v[140:143]
	v_add_u32_e32 v194, s31, v184
	s_add_i32 s73, s73, 2
	s_cmp_ge_u32 s73, s45
	s_waitcnt vmcnt(2)
	ds_write_b128 v194, v[144:147]
	s_cselect_b64 s[28:29], -1, 0
	ds_write_b128 v185, v[136:139] offset:36864
	s_waitcnt vmcnt(1)
	ds_write_b128 v185, v[132:135] offset:49152
	s_and_b64 vcc, exec, s[28:29]
	s_waitcnt lgkmcnt(6)
	v_mfma_f32_32x32x16_bf16 v[80:95], v[240:243], v[244:247], v[80:95]
	ds_read_b128 v[240:243], v181
	s_waitcnt vmcnt(0)
	ds_write_b128 v186, v[128:131] offset:36864
	v_mfma_f32_32x32x16_bf16 v[64:79], v[248:251], v[244:247], v[64:79]
	ds_read_b128 v[248:251], v187 offset:12288
	ds_read_b128 v[244:247], v189 offset:24576
	s_cbranch_vccnz .Lattn_noloadp
	s_mov_b32 s18, 0xfffe0000
	s_mov_b32 s19, -1
	v_lshl_add_u64 v[128:129], v[168:169], 0, s[18:19]
	global_load_dwordx4 v[140:143], v[128:129], off
	global_load_dwordx4 v[136:139], v[128:129], off offset:-256
	global_load_dwordx4 v[144:147], v[168:169], off
	global_load_dwordx4 v[132:135], v[168:169], off offset:-256
	s_nop 0
	global_load_dwordx4 v[128:131], v[166:167], off

; __device__ __forceinline__ void finishSM(f32x16& p0, f32x16& p1, float alpha, float& l_reg, bf16x8& pa0, bf16x8& pa1, bf16x8& pa2, bf16x8& pa3) {
; #pragma unroll
;   for (int r = 0; r < 16; ++r) p1[r] = __builtin_amdgcn_exp2f(p1[r]);
;   float ps = 0;
; #pragma unroll
;   for (int r = 0; r < 16; ++r) ps += p0[r];
; #pragma unroll
;   for (int r = 0; r < 16; ++r) ps += p1[r];
;   { auto rr = __builtin_amdgcn_permlane32_swap(__float_as_uint(ps), __float_as_uint(ps), false, false);
;     ps = __uint_as_float(rr[0]) + __uint_as_float(rr[1]); }
;   l_reg = l_reg * alpha + ps;
;     ...
;   PK4(p0, 0, pa0); PK4(p0, 8, pa1); PK4(p1, 0, pa2); PK4(p1, 8, pa3);
;     ...
; }
; __device__ __forceinline__ void qkt(f32x16& p0, f32x16& p1, const char* Ks, const bf16x8* qr, const char* qrl, int r32, int hi) {
;   p0 = f32x16{}; p1 = f32x16{};
; #pragma unroll
;   for (int d0 = 0; d0 < 8; ++d0) { int cb = (d0 * 16 + hi * 8) * 2;
;     bf16x8 b0 = *reinterpret_cast<const bf16x8*>(Ks + KSWZ(r32, cb));
;     bf16x8 b1 = *reinterpret_cast<const bf16x8*>(Ks + KSWZ(32 + r32, cb));
;     p0 = __builtin_amdgcn_mfma_f32_32x32x16_bf16(b0, qr[d0], p0, 0, 0, 0);
;     p1 = __builtin_amdgcn_mfma_f32_32x32x16_bf16(b1, qr[d0], p1, 0, 0, 0); }
; #pragma unroll
;   for (int d0 = 8; d0 < 12; ++d0) { int cb = (d0 * 16 + hi * 8) * 2;
;     bf16x8 b0 = *reinterpret_cast<const bf16x8*>(Ks + KSWZ(r32, cb));
;     bf16x8 b1 = *reinterpret_cast<const bf16x8*>(Ks + KSWZ(32 + r32, cb));
;     bf16x8 qf = *reinterpret_cast<const bf16x8*>(qrl + (((2 * (d0 - 8) + hi) ^ ((r32 >> 1) & 7)) << 4));
;     p0 = __builtin_amdgcn_mfma_f32_32x32x16_bf16(b0, qf, p0, 0, 0, 0);
;     p1 = __builtin_amdgcn_mfma_f32_32x32x16_bf16(b1, qf, p1, 0, 0, 0); }
; }
.Lattn_steady:
	v_exp_f32_e32 v225, v225
	v_exp_f32_e32 v228, v228
	v_exp_f32_e32 v226, v226
	v_add_f32_e32 v211, v225, v228
	s_waitcnt lgkmcnt(3)
	v_mfma_f32_32x32x16_bf16 v[80:95], v[236:239], v[124:127], 0
	ds_read_b128 v[236:239], v206 offset:49152
	v_exp_f32_e32 v229, v229
	v_add_f32_e32 v211, v226, v211
	v_exp_f32_e32 v227, v227
	v_add_f32_e32 v211, v229, v211
	v_mfma_f32_32x32x16_bf16 v[64:79], v[240:243], v[124:127], 0
	ds_read_b128 v[240:243], v208 offset:36864
	v_exp_f32_e32 v230, v230
	v_add_f32_e32 v211, v227, v211
	v_exp_f32_e32 v223, v223
	v_add_f32_e32 v211, v230, v211
	s_waitcnt lgkmcnt(3)
	v_mfma_f32_32x32x16_bf16 v[80:95], v[248:251], v[120:123], v[80:95]
	ds_read_b128 v[248:251], v208 offset:49152
	v_exp_f32_e32 v224, v224
	v_add_f32_e32 v211, v223, v211
	v_exp_f32_e32 v219, v219
	v_add_f32_e32 v211, v224, v211
	v_mfma_f32_32x32x16_bf16 v[64:79], v[244:247], v[120:123], v[64:79]
	ds_read_b128 v[244:247], v207 offset:36864
	v_exp_f32_e32 v221, v221
	v_add_f32_e32 v211, v219, v211
	v_exp_f32_e32 v220, v220
	v_add_f32_e32 v211, v221, v211
	s_waitcnt lgkmcnt(3)
	v_mfma_f32_32x32x16_bf16 v[80:95], v[232:235], v[116:119], v[80:95]
	ds_read_b128 v[232:235], v207 offset:49152
	v_exp_f32_e32 v222, v222
	v_add_f32_e32 v211, v220, v211
	v_exp_f32_e32 v215, v215
	v_add_f32_e32 v211, v222, v211
	v_mfma_f32_32x32x16_bf16 v[64:79], v[236:239], v[116:119], v[64:79]
	ds_read_b128 v[236:239], v204 offset:36864
	v_exp_f32_e32 v217, v217
	v_add_f32_e32 v211, v215, v211
	v_exp_f32_e32 v216, v216
	v_add_f32_e32 v211, v217, v211
	s_waitcnt lgkmcnt(3)
	v_mfma_f32_32x32x16_bf16 v[80:95], v[240:243], v[112:115], v[80:95]
	ds_read_b128 v[240:243], v204 offset:49152
	v_exp_f32_e32 v218, v218
	v_add_f32_e32 v211, v216, v211
	v_exp_f32_e32 v162, v162
	v_add_f32_e32 v211, v218, v211
	v_mfma_f32_32x32x16_bf16 v[64:79], v[248:251], v[112:115], v[64:79]
	ds_read_b128 v[248:251], v203 offset:36864
	v_exp_f32_e32 v163, v163
	v_exp_f32_e32 v160, v160
	v_exp_f32_e32 v161, v161
	s_waitcnt lgkmcnt(3)
	v_mfma_f32_32x32x16_bf16 v[80:95], v[244:247], v[108:111], v[80:95]
	ds_read_b128 v[244:247], v203 offset:49152
	v_exp_f32_e32 v158, v158
	v_exp_f32_e32 v159, v159
	v_exp_f32_e32 v156, v156
	v_mfma_f32_32x32x16_bf16 v[64:79], v[232:235], v[108:111], v[64:79]
	ds_read_b128 v[232:235], v200 offset:36864
	v_exp_f32_e32 v157, v157
	v_exp_f32_e32 v154, v154
	v_exp_f32_e32 v155, v155
	s_waitcnt lgkmcnt(3)
	v_mfma_f32_32x32x16_bf16 v[80:95], v[236:239], v[104:107], v[80:95]
	ds_read_b128 v[236:239], v200 offset:49152
	v_exp_f32_e32 v152, v152
	v_exp_f32_e32 v153, v153
	v_exp_f32_e32 v150, v150
	v_mfma_f32_32x32x16_bf16 v[64:79], v[240:243], v[104:107], v[64:79]
	ds_read_b128 v[240:243], v191 offset:36864
	v_exp_f32_e32 v151, v151
	v_exp_f32_e32 v148, v148
	v_exp_f32_e32 v149, v149
	s_waitcnt lgkmcnt(3)
	v_mfma_f32_32x32x16_bf16 v[80:95], v[248:251], v[100:103], v[80:95]
	ds_read_b128 v[248:251], v202 offset:49152
	v_add_f32_e32 v212, v162, v163
	v_add_f32_e32 v212, v160, v212
	v_add_f32_e32 v212, v161, v212
	v_add_f32_e32 v212, v158, v212
	v_add_f32_e32 v212, v159, v212
	v_add_f32_e32 v212, v156, v212
	v_mfma_f32_32x32x16_bf16 v[64:79], v[244:247], v[100:103], v[64:79]
	ds_read_b128 v[244:247], v182
	v_add_f32_e32 v212, v157, v212
	v_add_f32_e32 v212, v154, v212
	v_add_f32_e32 v212, v155, v212
	v_add_f32_e32 v212, v152, v212
	v_add_f32_e32 v212, v153, v212
	v_add_f32_e32 v212, v150, v212
	s_waitcnt lgkmcnt(3)
	v_mfma_f32_32x32x16_bf16 v[80:95], v[232:235], v[96:99], v[80:95]
	ds_read_b128 v[232:235], v198 offset:36864
	v_add_f32_e32 v212, v151, v212
	v_add_f32_e32 v212, v148, v212
	v_add_f32_e32 v212, v149, v212
	v_add_f32_e32 v211, v211, v212
	v_mov_b32_e32 v212, v211
	s_lshl_b32 s19, s18, 14
	v_add_u32_e32 v231, s19, v183
	s_waitcnt vmcnt(4)
	v_mfma_f32_32x32x16_bf16 v[64:79], v[236:239], v[96:99], v[64:79]
	ds_read_b128 v[236:239], v201 offset:49152
	ds_write_b128 v231, v[140:143]
	v_add_u32_e32 v140, s19, v184
	s_waitcnt vmcnt(2)
	ds_write_b128 v140, v[144:147]
	ds_write_b128 v185, v[136:139] offset:12288
	s_waitcnt vmcnt(1)
	ds_write_b128 v185, v[132:135] offset:24576
	s_mov_b32 s18, 0xfffa0000
	s_waitcnt lgkmcnt(6)
	v_mfma_f32_32x32x16_bf16 v[80:95], v[240:243], v[244:247], v[80:95]
	ds_read_b128 v[240:243], v181
	s_waitcnt vmcnt(0)
; __device__ __forceinline__ void partialSM(f32x16& p0, f32x16& p1, float& m_reg, float& mn, float& alpha) {
;     ...
;   for (int r = 1; r < 16; ++r) pmax = fmaxf(pmax, p0[r]);
; #pragma unroll
;   for (int r = 0; r < 16; ++r) pmax = fmaxf(pmax, p1[r]);
;   { auto rr = __builtin_amdgcn_permlane32_swap(__float_as_uint(pmax), __float_as_uint(pmax), false, false);
;     pmax = fmaxf(__uint_as_float(rr[0]), __uint_as_float(rr[1])); }
;   if (__builtin_expect(__all(pmax - m_reg <= THR / SCALE), 1)) { mn = m_reg; alpha = 1.f; }
;   else { mn = fmaxf(m_reg, pmax); alpha = __builtin_amdgcn_exp2f((m_reg - mn) * C); m_reg = mn; }
;   float mnC = -mn * C;
; #pragma unroll
;   for (int r = 0; r < 16; ++r) p0[r] = fmaf(p0[r], C, mnC);
; #pragma unroll
;   for (int r = 0; r < 16; ++r) p1[r] = fmaf(p1[r], C, mnC);
; #pragma unroll
;   for (int r = 0; r < 16; ++r) p0[r] = __builtin_amdgcn_exp2f(p0[r]);
; }
; __device__ __forceinline__ void finishSM(f32x16& p0, f32x16& p1, float alpha, float& l_reg, bf16x8& pa0, bf16x8& pa1, bf16x8& pa2, bf16x8& pa3) {
; #pragma unroll
;   for (int r = 0; r < 16; ++r) p1[r] = __builtin_amdgcn_exp2f(p1[r]);
;   float ps = 0;
; #pragma unroll
;   for (int r = 0; r < 16; ++r) ps += p0[r];
; #pragma unroll
;   for (int r = 0; r < 16; ++r) ps += p1[r];
;   { auto rr = __builtin_amdgcn_permlane32_swap(__float_as_uint(ps), __float_as_uint(ps), false, false);
;     ps = __uint_as_float(rr[0]) + __uint_as_float(rr[1]); }
;   l_reg = l_reg * alpha + ps;
;     ...
;   PK4(p0, 0, pa0); PK4(p0, 8, pa1); PK4(p1, 0, pa2); PK4(p1, 8, pa3);
;     ...
; }
; __device__ __forceinline__ void qkt(f32x16& p0, f32x16& p1, const char* Ks, const bf16x8* qr, const char* qrl, int r32, int hi) {
;   p0 = f32x16{}; p1 = f32x16{};
; #pragma unroll
;   for (int d0 = 0; d0 < 8; ++d0) { int cb = (d0 * 16 + hi * 8) * 2;
;     bf16x8 b0 = *reinterpret_cast<const bf16x8*>(Ks + KSWZ(r32, cb));
;     bf16x8 b1 = *reinterpret_cast<const bf16x8*>(Ks + KSWZ(32 + r32, cb));
;     p0 = __builtin_amdgcn_mfma_f32_32x32x16_bf16(b0, qr[d0], p0, 0, 0, 0);
;     p1 = __builtin_amdgcn_mfma_f32_32x32x16_bf16(b1, qr[d0], p1, 0, 0, 0); }
; #pragma unroll
;   for (int d0 = 8; d0 < 12; ++d0) { int cb = (d0 * 16 + hi * 8) * 2;
;     bf16x8 b0 = *reinterpret_cast<const bf16x8*>(Ks + KSWZ(r32, cb));
;     bf16x8 b1 = *reinterpret_cast<const bf16x8*>(Ks + KSWZ(32 + r32, cb));
	ds_write_b128 v186, v[128:131] offset:12288
	s_mov_b32 s19, -1
	v_lshl_add_u64 v[128:129], v[168:169], 0, s[18:19]
	s_mov_b32 s18, 0xfffc0000
	v_lshl_add_u64 v[130:131], v[168:169], 0, s[18:19]
	global_load_dwordx4 v[140:143], v[128:129], off
	global_load_dwordx4 v[136:139], v[128:129], off offset:-256
	v_mfma_f32_32x32x16_bf16 v[64:79], v[248:251], v[244:247], v[64:79]
	ds_read_b128 v[248:251], v187 offset:36864
	ds_read_b128 v[244:247], v189 offset:49152
	global_load_dwordx4 v[144:147], v[130:131], off
	global_load_dwordx4 v[132:135], v[130:131], off offset:-256
	s_movk_i32 s18, 0xe000
	v_lshl_add_u64 v[128:129], v[166:167], 0, s[18:19]
	global_load_dwordx4 v[128:131], v[128:129], off
	v_cvt_pk_bf16_f32 v158, v158, v159
	v_cvt_pk_bf16_f32 v159, v156, v157
	s_waitcnt lgkmcnt(3)
	v_mfma_f32_32x32x16_bf16 v[80:95], v[232:235], v[240:243], v[80:95]
	ds_read_b128 v[232:235], v179
	v_permlane32_swap_b32_e32 v211, v212
	v_cvt_pk_bf16_f32 v156, v162, v163
	v_cvt_pk_bf16_f32 v157, v160, v161
	v_cvt_pk_bf16_f32 v160, v154, v155
	v_cvt_pk_bf16_f32 v161, v152, v153
	v_cvt_pk_bf16_f32 v162, v150, v151
	v_mfma_f32_32x32x16_bf16 v[64:79], v[236:239], v[240:243], v[64:79]
	ds_read_b128 v[236:239], v188 offset:36864
	ds_read_b128 v[240:243], v190 offset:49152
	v_cvt_pk_bf16_f32 v163, v148, v149
	v_add_f32_e32 v211, v211, v212
	v_cvt_pk_bf16_f32 v148, v225, v228
	v_cvt_pk_bf16_f32 v149, v226, v229
	v_cvt_pk_bf16_f32 v150, v227, v230
	v_cvt_pk_bf16_f32 v151, v223, v224
	s_waitcnt lgkmcnt(2)
	v_mfma_f32_32x32x16_bf16 v[80:95], v[248:251], v[232:235], v[80:95]
	ds_read_b128 v[248:251], v177
	v_cvt_pk_bf16_f32 v152, v219, v221
	v_cvt_pk_bf16_f32 v153, v220, v222
	v_cvt_pk_bf16_f32 v154, v215, v217
	v_cvt_pk_bf16_f32 v155, v216, v218
	v_fma_f32 v176, v209, v176, v211
	v_mfma_f32_32x32x16_bf16 v[64:79], v[244:247], v[232:235], v[64:79]
	s_waitcnt lgkmcnt(0)
	v_mfma_f32_32x32x16_bf16 v[80:95], v[236:239], v[248:251], v[80:95]
	v_mfma_f32_32x32x16_bf16 v[64:79], v[240:243], v[248:251], v[64:79]
	s_lshl_b32 s31, s30, 14
	v_add_u32_e32 v180, s31, v178
	ds_read_b64_tr_b16 v[232:233], v180 offset:0
	ds_read_b64_tr_b16 v[234:235], v180 offset:2048
	ds_read_b64_tr_b16 v[236:237], v180 offset:512
	ds_read_b64_tr_b16 v[238:239], v180 offset:2560
	ds_read_b64_tr_b16 v[240:241], v180 offset:1024
	ds_read_b64_tr_b16 v[242:243], v180 offset:3072
	ds_read_b64_tr_b16 v[248:249], v180 offset:1536
	ds_read_b64_tr_b16 v[250:251], v180 offset:3584
	ds_read_b64_tr_b16 v[244:245], v180 offset:4096
	ds_read_b64_tr_b16 v[246:247], v180 offset:6144
	s_nop 3
	v_max3_f32 v194, v80, v81, v82
	v_max3_f32 v195, v64, v65, v66
	v_max3_f32 v194, v194, v83, v84
	v_max3_f32 v195, v195, v67, v68
	s_waitcnt lgkmcnt(6)
	v_mfma_f32_32x32x16_bf16 v[32:47], v[148:151], v[232:235], v[32:47]
	ds_read_b64_tr_b16 v[232:233], v180 offset:4608
	ds_read_b64_tr_b16 v[234:235], v180 offset:6656
	v_max3_f32 v194, v194, v85, v86
	v_max3_f32 v195, v195, v69, v70
	v_max3_f32 v194, v194, v87, v88
	v_max3_f32 v195, v195, v71, v72
	v_mfma_f32_32x32x16_bf16 v[48:63], v[148:151], v[236:239], v[48:63]
	ds_read_b64_tr_b16 v[236:237], v180 offset:5120
	ds_read_b64_tr_b16 v[238:239], v180 offset:7168
	v_max3_f32 v194, v194, v89, v90
	v_max3_f32 v195, v195, v73, v74
	v_max3_f32 v194, v194, v91, v92
	v_max3_f32 v195, v195, v75, v76
	s_waitcnt lgkmcnt(6)
	v_mfma_f32_32x32x16_bf16 v[16:31], v[148:151], v[240:243], v[16:31]
	ds_read_b64_tr_b16 v[240:241], v180 offset:5632
	ds_read_b64_tr_b16 v[242:243], v180 offset:7680
	v_max3_f32 v194, v194, v93, v94
	v_max3_f32 v195, v195, v77, v78
	v_max3_f32 v194, v194, v95, v195
	v_max_f32_e32 v194, v194, v79
	v_mfma_f32_32x32x16_bf16 v[0:15], v[148:151], v[248:251], v[0:15]
	ds_read_b64_tr_b16 v[248:249], v180 offset:8192
	ds_read_b64_tr_b16 v[250:251], v180 offset:10240
	v_mov_b32_e32 v195, v194
	s_nop 1
	v_permlane32_swap_b32_e32 v194, v195
	v_max_f32_e32 v194, v194, v195
	s_waitcnt lgkmcnt(6)
	v_mfma_f32_32x32x16_bf16 v[32:47], v[152:155], v[244:247], v[32:47]
	ds_read_b64_tr_b16 v[244:245], v180 offset:8704
	ds_read_b64_tr_b16 v[246:247], v180 offset:10752
	v_sub_f32_e32 v195, v194, v210
	v_cmp_ge_f32_e32 vcc, s15, v195
	v_mfma_f32_32x32x16_bf16 v[48:63], v[152:155], v[232:235], v[48:63]
	ds_read_b64_tr_b16 v[232:233], v180 offset:9216
	ds_read_b64_tr_b16 v[234:235], v180 offset:11264
	s_cmp_eq_u64 vcc, exec
	s_cselect_b64 s[40:41], -1, 0
	s_cbranch_scc1 .Lattn_fast1
	v_max_f32_e32 v194, v210, v194
	v_sub_f32_e32 v195, v210, v194
	v_mul_f32_e32 v195, 0x3dd53b94, v195
	v_exp_f32_e32 v214, v195
	v_mov_b32_e32 v210, v194
	s_branch .Lattn_join1
